# v30: v29 + in-proj->up-proj seam as arrive + group wait (TOP1 gates fcumsum and each workgroup's first attention unit; no invalidate)
# speedup vs baseline: 1.0575x; 1.0065x over previous
; #define LAS __attribute__((address_space(3)))
; __device__ __forceinline__ int opaque_tid(int wv) { unsigned z = 0u; asm volatile("" : "+v"(z)); return (wv << 6) | (int)__builtin_amdgcn_mbcnt_hi(~0u, __builtin_amdgcn_mbcnt_lo(~0u, z)); }
; __device__ __forceinline__ unsigned xb_add(unsigned* p, unsigned v) { return __hip_atomic_fetch_add(p, v, __ATOMIC_RELAXED, __HIP_MEMORY_SCOPE_AGENT); }
; __device__ __forceinline__ unsigned xb_xcc_id() { return (unsigned)__builtin_amdgcn_s_getreg((3 << 11) | 20) & 0xFu; }
; __global__ void __launch_bounds__(512) fwd_megakernel(Args A) {
;     extern __shared__ __attribute__((aligned(16))) unsigned char lds_raw[];
;     LAS unsigned char* lds = (LAS unsigned char*)lds_raw;
;     const int G = gridDim.x, bx = blockIdx.x;
;     const int wv = __builtin_amdgcn_readfirstlane((int)threadIdx.x >> 6);
;     unsigned char* ws = A.ws;
;     const int lo = A.ph_lo, hi = A.ph_hi;
;     ...
;     cg::grid_group grid = cg::this_grid();
;     unsigned* xbar = (unsigned*)(ws + WS_CTL) + 1024;
;     volatile LAS unsigned* xst = (volatile LAS unsigned*)(lds + MISC_OFF + 64);
;     { const int t0_ = opaque_tid(wv); if (t0_ == 0) { xst[0] = 0u; xst[1] = 0u; (void)xb_add(&xbar[XB_XCNT(xb_xcc_id())], 1u); } }
.LBB0_181:
.LBB0_182:
	v_writelane_b32 v255, 0, 11
	v_writelane_b32 v255, 0, 12
	s_mov_b64 s[2:3], exec
	s_mov_b64 exec, 1
	s_and_b32 s4, s86, 7
	s_lshl_b32 s4, s4, 8
	s_add_u32 s4, s4, 0x6000
	s_add_u32 s4, s60, s4
	s_addc_u32 s5, s61, 0
	v_mov_b32_e32 v2, 0
	global_load_dword v3, v2, s[4:5] sc1
	s_waitcnt vmcnt(0)
	v_readfirstlane_b32 s6, v3
	s_mov_b64 exec, s[2:3]
	s_bcnt1_i32_b32 s6, s6
	v_readlane_b32 s7, v251, 2
	s_mov_b32 s100, 0
	s_mov_b32 s101, 0
	s_cmpk_lg_i32 s7, 0x100
	s_cbranch_scc1 .Lmode_done
	s_mov_b32 s100, 1
	s_cmp_lg_u32 s6, 1
	s_cbranch_scc1 .Lmode_done
	s_mov_b32 s100, 2

; #define LAS __attribute__((address_space(3)))
; __device__ __forceinline__ unsigned xb_ld(unsigned* p)              { return __hip_atomic_load(p, __ATOMIC_RELAXED, __HIP_MEMORY_SCOPE_AGENT); }
; __device__ __forceinline__ unsigned xb_add(unsigned* p, unsigned v) { return __hip_atomic_fetch_add(p, v, __ATOMIC_RELAXED, __HIP_MEMORY_SCOPE_AGENT); }
; __device__ __forceinline__ unsigned xb_xcc_id() { return (unsigned)__builtin_amdgcn_s_getreg((3 << 11) | 20) & 0xFu; }
; #define XB_SPIN(cond, bar) do { unsigned _sp = 0; while (cond) { __builtin_amdgcn_s_sleep(1); \
;     if ((++_sp & 255u) == 0u) { if (xb_ld(&(bar)[XB_TMO])) break; if (_sp > XB_SPIN_CAP) { atomicAdd(&(bar)[XB_TMO], 1u); break; } } } } while (0)
; #define SEAM(k) do { } while (0)
; #define SEAM(k) do { if (lo <= (k) && (k) + 1 < hi) { if (hi > 1000) grid.sync(); else xcd_barrier(xbar, xst, opaque_tid(wv) == 0); } } while (0)
; __device__ __forceinline__ void xcd_barrier(unsigned* bar, volatile LAS unsigned* st, bool is0) {
;     asm volatile("s_waitcnt vmcnt(0)" ::: "memory");
;     __syncthreads();
;     if (is0) {
;         __builtin_amdgcn_s_waitcnt(0);
;         const unsigned x = xb_xcc_id();
;         unsigned nloc = st[0], nx = st[1];
;         if (nloc == 0u) { xcd_barrier_complete(bar, x, nloc, nx); st[0] = nloc; st[1] = nx; }
;         const unsigned old = xb_add(&bar[XB_XSUB(x)], 1u);
;         const unsigned gen = old / nloc;
;         if (old + 1u == (gen + 1u) * nloc) {
;             __builtin_amdgcn_fence(__ATOMIC_RELEASE, "agent");
;             asm volatile("s_waitcnt vmcnt(0)" ::: "memory");
;             const unsigned og = xb_add(&bar[XB_TOP], 1u);
;             const unsigned tg = og / nx;
;             if (og + 1u == (tg + 1u) * nx) xb_add(&bar[XB_TOPGEN], 1u);
;             else XB_SPIN(xb_ld(&bar[XB_TOPGEN]) == tg, bar);
;             __builtin_amdgcn_fence(__ATOMIC_ACQUIRE, "agent");
;             xb_add(&bar[XB_XGEN(x)], 1u);
;             asm volatile("s_waitcnt vmcnt(0)" ::: "memory");
;         } else {
;             XB_SPIN(xb_ld(&bar[XB_XGEN(x)]) == gen, bar);
;             __builtin_amdgcn_fence(__ATOMIC_ACQUIRE, "agent");
;             asm volatile("s_waitcnt vmcnt(0)" ::: "memory");
;         }
;     }
;     __syncthreads();
; }
; __global__ void __launch_bounds__(512) fwd_megakernel(Args A) {
;     ...
;             SEAM(P + 1);
.LBB0_279:
	v_readlane_b32 s0, v254, 45
	v_readlane_b32 s4, v251, 41
	s_or_b32 s0, s0, 3
	v_readlane_b32 s11, v251, 48
	s_cmp_ge_i32 s0, s11
	v_readlane_b32 s1, v254, 46
	v_readlane_b32 s5, v251, 42
	v_readlane_b32 s6, v251, 43
	v_readlane_b32 s7, v251, 44
	v_readlane_b32 s8, v251, 45
	v_readlane_b32 s9, v251, 46
	v_readlane_b32 s10, v251, 47
	s_cbranch_scc1 .LBB0_346
	v_readlane_b32 s4, v252, 13
	v_readlane_b32 s5, v252, 14
	s_mov_b64 s[2:3], -1
	s_and_b64 vcc, exec, s[4:5]
	s_cbranch_vccz .LBB0_334
	s_cmp_eq_u32 s100, 0
	s_cbranch_scc1 .Lsb_orig
	s_waitcnt vmcnt(0) lgkmcnt(0)
	s_barrier
	s_cmp_lg_u32 s94, 0
	s_cbranch_scc1 .Lsb_join
	s_mov_b64 exec, 1
	v_readlane_b32 s8, v251, 45
	v_readlane_b32 s9, v251, 46
	v_readlane_b32 s6, v251, 50
	v_mov_b32_e32 v4, 1
	v_mov_b32_e32 v8, 0
	s_and_b32 s6, s6, 7
	s_lshl_b32 s6, s6, 6
	s_add_u32 s6, s6, 0x6a00
	s_add_u32 s10, s8, s6
	s_addc_u32 s11, s9, 0
	s_add_u32 s8, s8, 0x6c40
	s_addc_u32 s9, s9, 0
	s_add_u32 s12, s80, 1
	s_lshl_b32 s13, s12, 5
	s_cmp_eq_u32 s100, 2
	s_cbranch_scc1 .Lsb_arr
	buffer_wbl2 sc1
	s_waitcnt vmcnt(0)

; #define LAS __attribute__((address_space(3)))
; __device__ __forceinline__ unsigned xb_ld(unsigned* p)              { return __hip_atomic_load(p, __ATOMIC_RELAXED, __HIP_MEMORY_SCOPE_AGENT); }
; __device__ __forceinline__ unsigned xb_add(unsigned* p, unsigned v) { return __hip_atomic_fetch_add(p, v, __ATOMIC_RELAXED, __HIP_MEMORY_SCOPE_AGENT); }
; __device__ __forceinline__ unsigned xb_xcc_id() { return (unsigned)__builtin_amdgcn_s_getreg((3 << 11) | 20) & 0xFu; }
; #define XB_SPIN(cond, bar) do { unsigned _sp = 0; while (cond) { __builtin_amdgcn_s_sleep(1); \
;     if ((++_sp & 255u) == 0u) { if (xb_ld(&(bar)[XB_TMO])) break; if (_sp > XB_SPIN_CAP) { atomicAdd(&(bar)[XB_TMO], 1u); break; } } } } while (0)
; __device__ __forceinline__ void xcd_barrier(unsigned* bar, volatile LAS unsigned* st, bool is0) {
;     asm volatile("s_waitcnt vmcnt(0)" ::: "memory");
;     __syncthreads();
;     if (is0) {
;         __builtin_amdgcn_s_waitcnt(0);
;         const unsigned x = xb_xcc_id();
;         unsigned nloc = st[0], nx = st[1];
;         if (nloc == 0u) { xcd_barrier_complete(bar, x, nloc, nx); st[0] = nloc; st[1] = nx; }
;         const unsigned old = xb_add(&bar[XB_XSUB(x)], 1u);
;         const unsigned gen = old / nloc;
;         if (old + 1u == (gen + 1u) * nloc) {
;             __builtin_amdgcn_fence(__ATOMIC_RELEASE, "agent");
;             asm volatile("s_waitcnt vmcnt(0)" ::: "memory");
;             const unsigned og = xb_add(&bar[XB_TOP], 1u);
;             const unsigned tg = og / nx;
;             if (og + 1u == (tg + 1u) * nx) xb_add(&bar[XB_TOPGEN], 1u);
;             else XB_SPIN(xb_ld(&bar[XB_TOPGEN]) == tg, bar);
;             __builtin_amdgcn_fence(__ATOMIC_ACQUIRE, "agent");
;             xb_add(&bar[XB_XGEN(x)], 1u);
;             asm volatile("s_waitcnt vmcnt(0)" ::: "memory");
;         } else {
;             XB_SPIN(xb_ld(&bar[XB_XGEN(x)]) == gen, bar);
;             __builtin_amdgcn_fence(__ATOMIC_ACQUIRE, "agent");
;             asm volatile("s_waitcnt vmcnt(0)" ::: "memory");
;         }
;     }
;     __syncthreads();
; }
.Lsb_top:
	global_atomic_add v8, v4, s[8:9]
	s_branch .Lsb_acq

; #define LAS __attribute__((address_space(3)))
; __device__ __forceinline__ unsigned xb_ld(unsigned* p)              { return __hip_atomic_load(p, __ATOMIC_RELAXED, __HIP_MEMORY_SCOPE_AGENT); }
; __device__ __forceinline__ unsigned xb_add(unsigned* p, unsigned v) { return __hip_atomic_fetch_add(p, v, __ATOMIC_RELAXED, __HIP_MEMORY_SCOPE_AGENT); }
; __device__ __forceinline__ unsigned xb_xcc_id() { return (unsigned)__builtin_amdgcn_s_getreg((3 << 11) | 20) & 0xFu; }
; #define XB_SPIN(cond, bar) do { unsigned _sp = 0; while (cond) { __builtin_amdgcn_s_sleep(1); \
;     if ((++_sp & 255u) == 0u) { if (xb_ld(&(bar)[XB_TMO])) break; if (_sp > XB_SPIN_CAP) { atomicAdd(&(bar)[XB_TMO], 1u); break; } } } } while (0)
; __device__ __forceinline__ void xcd_barrier(unsigned* bar, volatile LAS unsigned* st, bool is0) {
;     asm volatile("s_waitcnt vmcnt(0)" ::: "memory");
;     __syncthreads();
;     if (is0) {
;         __builtin_amdgcn_s_waitcnt(0);
;         const unsigned x = xb_xcc_id();
;         unsigned nloc = st[0], nx = st[1];
;         if (nloc == 0u) { xcd_barrier_complete(bar, x, nloc, nx); st[0] = nloc; st[1] = nx; }
;         const unsigned old = xb_add(&bar[XB_XSUB(x)], 1u);
;         const unsigned gen = old / nloc;
;         if (old + 1u == (gen + 1u) * nloc) {
;             __builtin_amdgcn_fence(__ATOMIC_RELEASE, "agent");
;             asm volatile("s_waitcnt vmcnt(0)" ::: "memory");
;             const unsigned og = xb_add(&bar[XB_TOP], 1u);
;             const unsigned tg = og / nx;
;             if (og + 1u == (tg + 1u) * nx) xb_add(&bar[XB_TOPGEN], 1u);
;             else XB_SPIN(xb_ld(&bar[XB_TOPGEN]) == tg, bar);
;             __builtin_amdgcn_fence(__ATOMIC_ACQUIRE, "agent");
;             xb_add(&bar[XB_XGEN(x)], 1u);
;             asm volatile("s_waitcnt vmcnt(0)" ::: "memory");
;         } else {
;             XB_SPIN(xb_ld(&bar[XB_XGEN(x)]) == gen, bar);
;             __builtin_amdgcn_fence(__ATOMIC_ACQUIRE, "agent");
;             asm volatile("s_waitcnt vmcnt(0)" ::: "memory");
;         }
;     }
;     __syncthreads();
; }
.Lsb_w:
	s_sleep 1
	global_load_dword v6, v8, s[10:11] sc1
	s_add_u32 s16, s16, 1
	s_waitcnt vmcnt(0)
	v_readfirstlane_b32 s15, v6
	s_cmp_ge_u32 s15, s13
	s_cbranch_scc1 .Lsb_acq
	s_cmp_lt_u32 s16, 0x400000
	s_cbranch_scc1 .Lsb_w

; __device__ __forceinline__ int opaque_tid(int wv) { unsigned z = 0u; asm volatile("" : "+v"(z)); return (wv << 6) | (int)__builtin_amdgcn_mbcnt_hi(~0u, __builtin_amdgcn_mbcnt_lo(~0u, z)); }
; __device__ __forceinline__ void fcumsum_task(const float* __restrict__ LOGF, float* __restrict__ NF2, int bh, int lane) {
;     const int bb = bh >> 3, h = bh & 7;
;     const float* src = LOGF + ((size_t)bb * SEQ + 32 * lane) * 8 + h;
;     float v[32]; float tot = 0.f;
; #pragma unroll
;     for (int i = 0; i < 32; ++i) { tot += src[(size_t)i * 8]; v[i] = tot; }
; __global__ void __launch_bounds__(512) fwd_megakernel(Args A) {
;     ...
;             if (P3SEL & 1) { const int t_ = opaque_tid(wv); if (bx < 32 && (t_ >> 6) == 0) fcumsum_task((const float*)(ws + WS_LOGF), (float*)(ws + WS_NF2), bx, t_ & 63); }
.LBB0_348:
	s_andn2_b64 vcc, exec, s[2:3]
	s_cbranch_vccnz .LBB0_516
	v_mov_b32_e32 v0, v1
	v_readlane_b32 s0, v252, 53
	v_mbcnt_lo_u32_b32 v0, -1, v0
	v_mbcnt_hi_u32_b32 v3, -1, v0
	s_waitcnt lgkmcnt(0)
	v_or_b32_e32 v2, s94, v3
	v_cmp_gt_u32_e32 vcc, 64, v2
	v_readlane_b32 s1, v252, 54
	s_and_b64 s[0:1], s[0:1], vcc
	s_and_saveexec_b64 s[2:3], s[0:1]
	s_cbranch_execz .LBB0_351
	s_cmp_eq_u32 s100, 0
	s_cbranch_scc1 .Lfc2_skip
	s_mov_b64 s[10:11], exec
	s_mov_b64 exec, 1
	v_readlane_b32 s12, v251, 45
	v_readlane_b32 s13, v251, 46
	s_add_u32 s12, s12, 0x6c40
	s_addc_u32 s13, s13, 0
	s_add_u32 s14, s80, 1
	s_lshl_b32 s14, s14, 3
	v_mov_b32_e32 v4, 0
	s_mov_b32 s16, 0
.Lfc2_w:
	global_load_dword v5, v4, s[12:13] sc1
	s_add_u32 s16, s16, 1
	s_waitcnt vmcnt(0)
	v_readfirstlane_b32 s15, v5
	s_cmp_ge_u32 s15, s14
	s_cbranch_scc1 .Lfc2_done
	s_sleep 1
	s_cmp_lt_u32 s16, 0x400000
	s_cbranch_scc1 .Lfc2_w
.Lfc2_done:
	s_mov_b64 exec, s[10:11]
; __device__ __forceinline__ void fcumsum_task(const float* __restrict__ LOGF, float* __restrict__ NF2, int bh, int lane) {
;     const int bb = bh >> 3, h = bh & 7;
;     const float* src = LOGF + ((size_t)bb * SEQ + 32 * lane) * 8 + h;
;     float v[32]; float tot = 0.f;
; #pragma unroll
;     for (int i = 0; i < 32; ++i) { tot += src[(size_t)i * 8]; v[i] = tot; }
;     float inc = tot;
; #pragma unroll
;     for (int o = 1; o < 64; o <<= 1) { const float t = __builtin_bit_cast(float, __builtin_amdgcn_ds_bpermute(((lane - o) & 63) << 2, __builtin_bit_cast(int, inc))); if (lane >= o) inc += t; }
;     const float excl = inc - tot;
;     float* dst = NF2 + (size_t)bh * SEQ + 32 * lane;
; #pragma unroll
;     for (int i = 0; i < 32; ++i) dst[i] = -(excl + v[i]) * LOG2E;
; }
.Lfc2_skip:
	v_lshlrev_b32_e32 v0, 5, v3
	v_readlane_b32 s0, v252, 57
	v_lshlrev_b64 v[4:5], 5, v[0:1]
	v_readlane_b32 s1, v252, 58
	v_lshlrev_b32_e32 v3, 2, v3
	v_cmp_eq_u32_e32 vcc, 0, v2
	v_lshl_add_u64 v[4:5], s[0:1], 0, v[4:5]
	global_load_dword v6, v[4:5], off
	global_load_dword v7, v[4:5], off offset:32
	global_load_dword v8, v[4:5], off offset:64
	global_load_dword v9, v[4:5], off offset:96
	global_load_dword v10, v[4:5], off offset:128
	global_load_dword v11, v[4:5], off offset:160
	global_load_dword v12, v[4:5], off offset:192
	global_load_dword v13, v[4:5], off offset:224
	global_load_dword v14, v[4:5], off offset:256
	global_load_dword v15, v[4:5], off offset:288
	global_load_dword v16, v[4:5], off offset:320
	global_load_dword v17, v[4:5], off offset:352
	global_load_dword v18, v[4:5], off offset:384
	global_load_dword v19, v[4:5], off offset:416
	global_load_dword v20, v[4:5], off offset:448
	global_load_dword v21, v[4:5], off offset:480
	global_load_dword v22, v[4:5], off offset:512
	global_load_dword v23, v[4:5], off offset:544
	global_load_dword v24, v[4:5], off offset:576
	global_load_dword v25, v[4:5], off offset:608
	global_load_dword v26, v[4:5], off offset:640
	global_load_dword v27, v[4:5], off offset:672
	global_load_dword v28, v[4:5], off offset:704
	global_load_dword v29, v[4:5], off offset:736
	global_load_dword v30, v[4:5], off offset:768
	global_load_dword v31, v[4:5], off offset:800
	global_load_dword v32, v[4:5], off offset:832
	global_load_dword v33, v[4:5], off offset:864
	global_load_dword v34, v[4:5], off offset:896
	global_load_dword v35, v[4:5], off offset:928
	global_load_dword v36, v[4:5], off offset:960
	global_load_dword v37, v[4:5], off offset:992
	v_add_u32_e32 v4, 0xfc, v3
	v_and_b32_e32 v38, 0xfc, v4
	v_readlane_b32 s0, v252, 61
	v_readlane_b32 s1, v252, 62
	s_waitcnt vmcnt(0)
	v_add_f32_e32 v4, 0, v6
	v_add_f32_e32 v5, v4, v7
	v_add_f32_e32 v6, v5, v8
	v_add_f32_e32 v7, v6, v9
	v_add_f32_e32 v8, v7, v10
	v_add_f32_e32 v9, v8, v11
	v_add_f32_e32 v10, v9, v12
	v_add_f32_e32 v11, v10, v13
	v_add_f32_e32 v12, v11, v14
	v_add_f32_e32 v13, v12, v15
	v_add_f32_e32 v14, v13, v16
	v_add_f32_e32 v15, v14, v17
	v_add_f32_e32 v16, v15, v18
	v_add_f32_e32 v17, v16, v19
	v_add_f32_e32 v18, v17, v20
	v_add_f32_e32 v19, v18, v21
	v_add_f32_e32 v20, v19, v22
	v_add_f32_e32 v21, v20, v23
	v_add_f32_e32 v22, v21, v24
	v_add_f32_e32 v23, v22, v25
	v_add_f32_e32 v24, v23, v26
	v_add_f32_e32 v25, v24, v27
	v_add_f32_e32 v26, v25, v28
	v_add_f32_e32 v27, v26, v29
	v_add_f32_e32 v28, v27, v30
	v_add_f32_e32 v29, v28, v31
	v_add_f32_e32 v30, v29, v32
	v_add_f32_e32 v31, v30, v33
	v_add_f32_e32 v32, v31, v34
	v_add_f32_e32 v33, v32, v35
	v_add_f32_e32 v34, v33, v36
	v_add_f32_e32 v35, v34, v37
	ds_bpermute_b32 v36, v38, v35
	v_add_u32_e32 v37, 0xf8, v3
	v_and_b32_e32 v37, 0xfc, v37
	v_add_u32_e32 v38, 0xf0, v3
	v_and_b32_e32 v38, 0xfc, v38
	s_waitcnt lgkmcnt(0)
	v_add_f32_e32 v36, v35, v36
	v_cndmask_b32_e32 v36, v36, v35, vcc
	ds_bpermute_b32 v37, v37, v36
	v_cmp_gt_u32_e32 vcc, 2, v2
	s_waitcnt lgkmcnt(0)
	v_add_f32_e32 v37, v36, v37
	v_cndmask_b32_e32 v36, v37, v36, vcc
	ds_bpermute_b32 v37, v38, v36
	v_add_u32_e32 v38, 0xe0, v3
	v_cmp_gt_u32_e32 vcc, 4, v2
	v_and_b32_e32 v38, 0xfc, v38
	s_waitcnt lgkmcnt(0)
	v_add_f32_e32 v37, v36, v37
	v_cndmask_b32_e32 v36, v37, v36, vcc
	ds_bpermute_b32 v37, v38, v36
	v_add_u32_e32 v38, 0xc0, v3
	v_cmp_gt_u32_e32 vcc, 8, v2
	v_and_b32_e32 v38, 0xfc, v38
	v_xor_b32_e32 v3, 0x80, v3
	s_waitcnt lgkmcnt(0)
	v_add_f32_e32 v37, v36, v37
	v_cndmask_b32_e32 v36, v37, v36, vcc
	ds_bpermute_b32 v37, v38, v36
	v_cmp_gt_u32_e32 vcc, 16, v2
	s_waitcnt lgkmcnt(0)
	v_add_f32_e32 v37, v36, v37
	v_cndmask_b32_e32 v38, v37, v36, vcc
	ds_bpermute_b32 v3, v3, v38
	v_lshl_add_u64 v[36:37], v[0:1], 2, s[0:1]
	v_cmp_gt_u32_e32 vcc, 32, v2
	s_mov_b32 s0, 0xbfb8aa3b
	s_waitcnt lgkmcnt(0)
	v_add_f32_e32 v0, v38, v3
	v_cndmask_b32_e32 v0, v0, v38, vcc
	v_sub_f32_e32 v0, v0, v35
	v_pk_add_f32 v[2:3], v[4:5], v[0:1] op_sel_hi:[1,0]
	v_pk_add_f32 v[4:5], v[6:7], v[0:1] op_sel_hi:[1,0]
	v_pk_add_f32 v[6:7], v[8:9], v[0:1] op_sel_hi:[1,0]
	v_pk_add_f32 v[8:9], v[10:11], v[0:1] op_sel_hi:[1,0]
	v_pk_add_f32 v[10:11], v[12:13], v[0:1] op_sel_hi:[1,0]
	v_pk_add_f32 v[12:13], v[14:15], v[0:1] op_sel_hi:[1,0]
	v_pk_add_f32 v[14:15], v[16:17], v[0:1] op_sel_hi:[1,0]
	v_pk_add_f32 v[16:17], v[18:19], v[0:1] op_sel_hi:[1,0]
	v_pk_add_f32 v[18:19], v[20:21], v[0:1] op_sel_hi:[1,0]
	v_pk_add_f32 v[20:21], v[22:23], v[0:1] op_sel_hi:[1,0]
	v_pk_add_f32 v[22:23], v[24:25], v[0:1] op_sel_hi:[1,0]
	v_pk_add_f32 v[24:25], v[26:27], v[0:1] op_sel_hi:[1,0]
	v_pk_add_f32 v[26:27], v[28:29], v[0:1] op_sel_hi:[1,0]
	v_pk_add_f32 v[28:29], v[30:31], v[0:1] op_sel_hi:[1,0]
	v_pk_add_f32 v[30:31], v[32:33], v[0:1] op_sel_hi:[1,0]
	v_pk_add_f32 v[32:33], v[34:35], v[0:1] op_sel_hi:[1,0]
	v_pk_mul_f32 v[2:3], v[2:3], s[0:1] op_sel_hi:[1,0]
	v_pk_mul_f32 v[4:5], v[4:5], s[0:1] op_sel_hi:[1,0]
	v_pk_mul_f32 v[6:7], v[6:7], s[0:1] op_sel_hi:[1,0]
	v_pk_mul_f32 v[8:9], v[8:9], s[0:1] op_sel_hi:[1,0]
	v_pk_mul_f32 v[10:11], v[10:11], s[0:1] op_sel_hi:[1,0]
	v_pk_mul_f32 v[12:13], v[12:13], s[0:1] op_sel_hi:[1,0]
	v_pk_mul_f32 v[14:15], v[14:15], s[0:1] op_sel_hi:[1,0]
	v_pk_mul_f32 v[16:17], v[16:17], s[0:1] op_sel_hi:[1,0]
	v_pk_mul_f32 v[18:19], v[18:19], s[0:1] op_sel_hi:[1,0]
	v_pk_mul_f32 v[20:21], v[20:21], s[0:1] op_sel_hi:[1,0]
	v_pk_mul_f32 v[22:23], v[22:23], s[0:1] op_sel_hi:[1,0]
	v_pk_mul_f32 v[24:25], v[24:25], s[0:1] op_sel_hi:[1,0]
	v_pk_mul_f32 v[26:27], v[26:27], s[0:1] op_sel_hi:[1,0]
	v_pk_mul_f32 v[28:29], v[28:29], s[0:1] op_sel_hi:[1,0]
	v_pk_mul_f32 v[30:31], v[30:31], s[0:1] op_sel_hi:[1,0]
	v_pk_mul_f32 v[32:33], v[32:33], s[0:1] op_sel_hi:[1,0]
	global_store_dwordx4 v[36:37], v[2:5], off
	global_store_dwordx4 v[36:37], v[6:9], off offset:16
	global_store_dwordx4 v[36:37], v[10:13], off offset:32
	global_store_dwordx4 v[36:37], v[14:17], off offset:48
	global_store_dwordx4 v[36:37], v[18:21], off offset:64
	global_store_dwordx4 v[36:37], v[22:25], off offset:80
	global_store_dwordx4 v[36:37], v[26:29], off offset:96
	global_store_dwordx4 v[36:37], v[30:33], off offset:112

; __device__ __forceinline__ int opaque_tid(int wv) { unsigned z = 0u; asm volatile("" : "+v"(z)); return (wv << 6) | (int)__builtin_amdgcn_mbcnt_hi(~0u, __builtin_amdgcn_mbcnt_lo(~0u, z)); }
; __global__ void __launch_bounds__(512) fwd_megakernel(Args A) {
;     ...
;             for (int ui_ = 0;; ++ui_) {
;                 int idx;
;                 if (ATT_DYNQ) {
;                     if (ui_ == 0) idx = bx;
;                     else {
;                         if (opaque_tid(wv) == 0) *qslot = G + (int)atomicAdd(ctr, 1u);
;                         __syncthreads();
;                         idx = *qslot;
;                         __syncthreads();
;                     }
;                 } else {
;                     idx = (ui_ == 1) ? (511 - bx) : (ui_ * 256 + bx);
;                     if (ui_ >= 3 || G != 256) idx = 768;
;                 }
;                 if (idx >= 768) break;
;                 const int code = att_code(idx >> 5), bh = idx & 31, type = code >> 3, qb = code & 7, bb = bh >> 3, h = bh & 7;
;                 if (type == 0) attn_unit<0>(bb, h, qb, (const bf16_t*)(ws + WS_QM), (const bf16_t*)(ws + WS_KN), (const bf16_t*)(ws + WS_KR), (const bf16_t*)(ws + WS_VTM), nullptr, gout, (bf16_t*)(ws + WS_OB), lds, wv);
;                 else if (type == 1) attn_unit<1>(bb, h, qb, QK4, QK4 + QS, nullptr, (const bf16_t*)(ws + WS_VTS), nullptr, gout, (bf16_t*)(ws + WS_OB), lds, wv);
;                 else attn_unit<2>(bb, h, qb, QK4 + 2 * QS, QK4 + 3 * QS, nullptr, (const bf16_t*)(ws + WS_VTS) + (size_t)512 * MTOK, (const float*)(ws + WS_NF2), gout, (bf16_t*)(ws + WS_OB), lds, wv);
.LBB0_530:
	s_cmpk_gt_i32 s1, 0x2ff
	s_mov_b64 s[2:3], -1
	s_cbranch_scc1 .LBB0_523
	s_ashr_i32 s0, s1, 5
	s_add_i32 s4, s0, -12
	s_cmp_lt_i32 s0, 12
	s_mov_b32 s2, 0x214c742
	s_cselect_b32 s3, s2, 0x802320c
	s_mov_b32 s2, 0x54b635cf
	s_cselect_b32 s0, s0, s4
	s_cselect_b32 s2, s2, 0xe82ad877
	s_mul_i32 s0, s0, 5
	s_lshr_b64 s[2:3], s[2:3], s0
	v_writelane_b32 v254, s8, 59
	s_and_b32 s3, s2, 24
	s_and_b32 s0, s2, 7
	s_bfe_u32 s95, s1, 0x20003
	s_and_b32 s33, s1, 7
	s_lshl_b32 s4, s95, 3
	s_add_i32 s4, s4, s0
	v_writelane_b32 v255, s4, 8
	s_mov_b64 s[6:7], -1
	v_writelane_b32 v254, s3, 60
	s_cmp_eq_u32 s100, 0
	s_cbranch_scc1 .Lsv_skip
	v_readlane_b32 s2, v255, 12
	v_readlane_b32 s4, v254, 57
	s_add_u32 s4, s4, 1
	s_cmp_eq_u32 s2, s4
	s_cbranch_scc1 .Lsv_skip
	v_writelane_b32 v255, s4, 12
	s_cmp_lg_u32 s94, 0
	s_cbranch_scc1 .Lsv_join
	s_lshl_b32 s2, s4, 3
	v_readlane_b32 s4, v251, 45
	v_readlane_b32 s5, v251, 46
	s_add_u32 s4, s4, 0x6c40
	s_addc_u32 s5, s5, 0
	s_mov_b64 exec, 1
	v_mov_b32_e32 v2, 0
	v_mov_b32_e32 v4, 0

; __device__ __forceinline__ int opaque_tid(int wv) { unsigned z = 0u; asm volatile("" : "+v"(z)); return (wv << 6) | (int)__builtin_amdgcn_mbcnt_hi(~0u, __builtin_amdgcn_mbcnt_lo(~0u, z)); }
; __global__ void __launch_bounds__(512) fwd_megakernel(Args A) {
;     ...
;             for (int ui_ = 0;; ++ui_) {
;                 int idx;
;                 if (ATT_DYNQ) {
;                     if (ui_ == 0) idx = bx;
;                     else {
;                         if (opaque_tid(wv) == 0) *qslot = G + (int)atomicAdd(ctr, 1u);
;                         __syncthreads();
;                         idx = *qslot;
;                         __syncthreads();
;                     }
;                 } else {
;                     idx = (ui_ == 1) ? (511 - bx) : (ui_ * 256 + bx);
;                     if (ui_ >= 3 || G != 256) idx = 768;
;                 }
;                 if (idx >= 768) break;
;                 const int code = att_code(idx >> 5), bh = idx & 31, type = code >> 3, qb = code & 7, bb = bh >> 3, h = bh & 7;
;                 if (type == 0) attn_unit<0>(bb, h, qb, (const bf16_t*)(ws + WS_QM), (const bf16_t*)(ws + WS_KN), (const bf16_t*)(ws + WS_KR), (const bf16_t*)(ws + WS_VTM), nullptr, gout, (bf16_t*)(ws + WS_OB), lds, wv);
;                 else if (type == 1) attn_unit<1>(bb, h, qb, QK4, QK4 + QS, nullptr, (const bf16_t*)(ws + WS_VTS), nullptr, gout, (bf16_t*)(ws + WS_OB), lds, wv);
;                 else attn_unit<2>(bb, h, qb, QK4 + 2 * QS, QK4 + 3 * QS, nullptr, (const bf16_t*)(ws + WS_VTS) + (size_t)512 * MTOK, (const float*)(ws + WS_NF2), gout, (bf16_t*)(ws + WS_OB), lds, wv);
.Lsv_skip:
	s_cmp_eq_u32 s3, 8
	s_cbranch_scc1 .Lsw_skip
	s_cmp_eq_u32 s100, 0
	s_cbranch_scc1 .Lsw_skip
	v_readlane_b32 s2, v255, 11
	v_readlane_b32 s4, v254, 57
	s_add_u32 s4, s4, 1
	s_cmp_eq_u32 s2, s4
	s_cbranch_scc1 .Lsw_skip
	v_writelane_b32 v255, s4, 11
	s_cmp_lg_u32 s94, 0
	s_cbranch_scc1 .Lsw_join
	s_lshl_b32 s2, s4, 3
	v_readlane_b32 s4, v251, 45
	v_readlane_b32 s5, v251, 46
	s_add_u32 s4, s4, 0x6c00
	s_addc_u32 s5, s5, 0
	s_mov_b64 exec, 1
	v_mov_b32_e32 v2, 0
	v_mov_b32_e32 v4, 0
